# LN-stat prep of P6/P9/P10/P11 loads both row panels in one round trip; LN3 partner sync skips the poll for the last arriver
# baseline (speedup 1.0000x reference)
; #define LAS __attribute__((address_space(3)))
;     __device__ bool next(int i, Unit& u) const { const int nr = nwg / G; if (i >= nr) return false; return RegSched::next(nr - 1 - i, u); }
;     __device__ __forceinline__ static void stats_of(const f32x2* st, size_t row, int h, float& s, float& ss) {
;         const f32x4* sp = (const f32x4*)(st + row * 16 + h * 8); s = 0.f; ss = 0.f;
; #pragma unroll
;         for (int q = 0; q < 4; ++q) { const f32x4 v = sp[q]; s += v[0] + v[2]; ss += v[1] + v[3]; }
;     template <class Sched> __device__ __forceinline__ void prep(const Sched& S, LAS unsigned char* ldsx) {
;         Unit u; int t0 = 0, t1 = 0; bool any = S.next(0, u);
;         if (any) { t0 = u.row0; t1 = t0; for (int i = 1; S.next(i, u); ++i) if (u.row0 != t0) { t1 = u.row0; break; } }
;         tag0 = t0;
;         if (any) {
;             LAS f32x2* X = (LAS f32x2*)ldsx; int t = threadIdx.x; asm volatile("" : "+v"(t));
; #pragma unroll
;             for (int e = 0; e < 2; ++e) { float s, q; stats_of(st_in, (size_t)(e ? t1 : t0) + (t >> 1), t & 1, s, q);
;                 s += __shfl_xor(s, 1); q += __shfl_xor(q, 1);
;                 const float mean = s * (1.f / DM);
;                 if ((t & 1) == 0) X[e * 256 + (t >> 1)] = (f32x2){mean, __builtin_amdgcn_rsqf(fmaxf(q * (1.f / DM) - mean * mean, 0.f) + LN_EPS)}; }
;         }
.LBB0_918:
	v_mov_b32_e32 v2, v202
	s_ashr_i32 s7, s6, 31
	v_ashrrev_i32_e32 v0, 1, v2
	v_ashrrev_i32_e32 v1, 31, v0
	v_lshl_add_u64 v[4:5], v[0:1], 0, s[6:7]
	v_and_b32_e32 v22, 1, v2
	v_lshlrev_b64 v[4:5], 7, v[4:5]
	v_mov_b32_e32 v3, 0
	v_lshl_add_u64 v[4:5], s[14:15], 0, v[4:5]
	v_lshlrev_b32_e32 v2, 6, v22
	v_lshl_add_u64 v[8:9], v[4:5], 0, v[2:3]
	global_load_dwordx4 v[4:7], v[8:9], off
	global_load_dwordx4 v[10:13], v[8:9], off offset:16
	global_load_dwordx4 v[14:17], v[8:9], off offset:32
	global_load_dwordx4 v[18:21], v[8:9], off offset:48
	s_mov_b32 s98, s0
	s_ashr_i32 s99, s0, 31
	v_lshl_add_u64 v[40:41], v[0:1], 0, s[98:99]
	v_lshlrev_b64 v[40:41], 7, v[40:41]
	v_lshl_add_u64 v[40:41], s[14:15], 0, v[40:41]
	v_lshlrev_b32_e32 v42, 6, v22
	v_mov_b32_e32 v43, 0
	v_lshl_add_u64 v[40:41], v[40:41], 0, v[42:43]
	global_load_dwordx4 v[24:27], v[40:41], off
	global_load_dwordx4 v[28:31], v[40:41], off offset:16
	global_load_dwordx4 v[32:35], v[40:41], off offset:32
	global_load_dwordx4 v[36:39], v[40:41], off offset:48
	v_mbcnt_lo_u32_b32 v2, -1, 0
	v_mbcnt_hi_u32_b32 v2, -1, v2
	v_and_b32_e32 v9, 64, v2
	v_xor_b32_e32 v8, 1, v2
	v_add_u32_e32 v9, 64, v9
	v_cmp_lt_i32_e32 vcc, v8, v9
	s_add_i32 s1, 0, 0x20000
	v_lshl_add_u32 v9, v0, 3, s1
	v_cndmask_b32_e32 v2, v2, v8, vcc
	v_lshlrev_b32_e32 v8, 2, v2
	v_lshlrev_b32_e32 v2, 3, v22
	v_cmp_eq_u32_e32 vcc, 0, v22
	s_waitcnt vmcnt(7)
	v_pk_add_f32 v[4:5], v[4:5], v[6:7]
	s_waitcnt vmcnt(6)
	v_pk_add_f32 v[6:7], v[10:11], v[12:13]
	v_pk_add_f32 v[4:5], v[4:5], 0 op_sel_hi:[1,0]
	s_waitcnt vmcnt(5)
	v_pk_add_f32 v[10:11], v[14:15], v[16:17]
	v_pk_add_f32 v[4:5], v[4:5], v[6:7]
	s_waitcnt vmcnt(4)
	v_pk_add_f32 v[12:13], v[18:19], v[20:21]
	v_pk_add_f32 v[4:5], v[4:5], v[10:11]
	s_nop 0
	v_pk_add_f32 v[4:5], v[4:5], v[12:13]
	ds_bpermute_b32 v6, v8, v4
	ds_bpermute_b32 v7, v8, v5
	s_and_saveexec_b64 s[10:11], vcc
	s_cbranch_execz .LBB0_920
	s_waitcnt lgkmcnt(0)
	v_pk_add_f32 v[4:5], v[4:5], v[6:7]
	s_mov_b32 s4, 0x3a800000
	v_pk_mul_f32 v[4:5], v[4:5], s[4:5] op_sel_hi:[1,0]
	s_nop 0
	v_fma_f32 v5, -v4, v4, v5
	v_max_f32_e32 v5, 0, v5
	v_add_f32_e32 v5, 0x3727c5ac, v5
	v_rsq_f32_e32 v5, v5
	ds_write_b64 v9, v[4:5]
.LBB0_920:
	s_or_b64 exec, exec, s[10:11]
	s_waitcnt lgkmcnt(0)
	s_waitcnt vmcnt(3)
	v_pk_add_f32 v[0:1], v[24:25], v[26:27]
	s_waitcnt vmcnt(2)
	v_pk_add_f32 v[2:3], v[28:29], v[30:31]
	v_pk_add_f32 v[0:1], v[0:1], 0 op_sel_hi:[1,0]
	s_waitcnt vmcnt(1)
	v_pk_add_f32 v[4:5], v[32:33], v[34:35]
	v_pk_add_f32 v[0:1], v[0:1], v[2:3]
	s_waitcnt vmcnt(0)
	v_pk_add_f32 v[6:7], v[36:37], v[38:39]
	v_pk_add_f32 v[0:1], v[0:1], v[4:5]
	s_nop 0
	v_pk_add_f32 v[0:1], v[0:1], v[6:7]
	ds_bpermute_b32 v2, v8, v0
	ds_bpermute_b32 v3, v8, v1
	s_and_saveexec_b64 s[0:1], vcc
	s_cbranch_execz .LBB0_922
	s_waitcnt lgkmcnt(0)
	v_pk_add_f32 v[0:1], v[0:1], v[2:3]
	s_mov_b32 s4, 0x3a800000
	v_pk_mul_f32 v[0:1], v[0:1], s[4:5] op_sel_hi:[1,0]
	s_nop 0
	v_fma_f32 v1, -v0, v0, v1
	v_max_f32_e32 v1, 0, v1
	v_add_f32_e32 v1, 0x3727c5ac, v1
	v_rsq_f32_e32 v1, v1
	ds_write_b64 v9, v[0:1] offset:2048

; #define LAS __attribute__((address_space(3)))
;     __device__ bool next(int i, Unit& u) const { const int nr = nwg / G; if (i >= nr) return false; return RegSched::next(nr - 1 - i, u); }
;     __device__ __forceinline__ static void stats_of(const f32x2* st, size_t row, int h, float& s, float& ss) {
;         const f32x4* sp = (const f32x4*)(st + row * 16 + h * 8); s = 0.f; ss = 0.f;
; #pragma unroll
;         for (int q = 0; q < 4; ++q) { const f32x4 v = sp[q]; s += v[0] + v[2]; ss += v[1] + v[3]; }
;     template <class Sched> __device__ __forceinline__ void prep(const Sched& S, LAS unsigned char* ldsx) {
;         Unit u; int t0 = 0, t1 = 0; bool any = S.next(0, u);
;         if (any) { t0 = u.row0; t1 = t0; for (int i = 1; S.next(i, u); ++i) if (u.row0 != t0) { t1 = u.row0; break; } }
;         tag0 = t0;
;         if (any) {
;             LAS f32x2* X = (LAS f32x2*)ldsx; int t = threadIdx.x; asm volatile("" : "+v"(t));
; #pragma unroll
;             for (int e = 0; e < 2; ++e) { float s, q; stats_of(st_in, (size_t)(e ? t1 : t0) + (t >> 1), t & 1, s, q);
;                 s += __shfl_xor(s, 1); q += __shfl_xor(q, 1);
;                 const float mean = s * (1.f / DM);
;                 if ((t & 1) == 0) X[e * 256 + (t >> 1)] = (f32x2){mean, __builtin_amdgcn_rsqf(fmaxf(q * (1.f / DM) - mean * mean, 0.f) + LN_EPS)}; }
;         }
.LBB0_1231:
	v_mov_b32_e32 v2, v202
	s_ashr_i32 s21, s20, 31
	v_ashrrev_i32_e32 v0, 1, v2
	v_ashrrev_i32_e32 v1, 31, v0
	v_lshl_add_u64 v[4:5], v[0:1], 0, s[20:21]
	v_and_b32_e32 v22, 1, v2
	v_lshlrev_b64 v[4:5], 7, v[4:5]
	v_mov_b32_e32 v3, 0
	v_lshl_add_u64 v[4:5], s[14:15], 0, v[4:5]
	v_lshlrev_b32_e32 v2, 6, v22
	v_lshl_add_u64 v[8:9], v[4:5], 0, v[2:3]
	global_load_dwordx4 v[4:7], v[8:9], off
	global_load_dwordx4 v[10:13], v[8:9], off offset:16
	global_load_dwordx4 v[14:17], v[8:9], off offset:32
	global_load_dwordx4 v[18:21], v[8:9], off offset:48
	s_mov_b32 s98, s0
	s_ashr_i32 s99, s0, 31
	v_lshl_add_u64 v[40:41], v[0:1], 0, s[98:99]
	v_lshlrev_b64 v[40:41], 7, v[40:41]
	v_lshl_add_u64 v[40:41], s[14:15], 0, v[40:41]
	v_lshlrev_b32_e32 v42, 6, v22
	v_mov_b32_e32 v43, 0
	v_lshl_add_u64 v[40:41], v[40:41], 0, v[42:43]
	global_load_dwordx4 v[24:27], v[40:41], off
	global_load_dwordx4 v[28:31], v[40:41], off offset:16
	global_load_dwordx4 v[32:35], v[40:41], off offset:32
	global_load_dwordx4 v[36:39], v[40:41], off offset:48
	v_mbcnt_lo_u32_b32 v2, -1, 0
	v_mbcnt_hi_u32_b32 v2, -1, v2
	v_and_b32_e32 v9, 64, v2
	v_xor_b32_e32 v8, 1, v2
	v_add_u32_e32 v9, 64, v9
	v_cmp_lt_i32_e32 vcc, v8, v9
	s_add_i32 s1, 0, 0x20000
	v_lshl_add_u32 v9, v0, 3, s1
	v_cndmask_b32_e32 v2, v2, v8, vcc
	v_lshlrev_b32_e32 v8, 2, v2
	v_lshlrev_b32_e32 v2, 3, v22
	v_cmp_eq_u32_e32 vcc, 0, v22
	s_waitcnt vmcnt(7)
	v_pk_add_f32 v[4:5], v[4:5], v[6:7]
	s_waitcnt vmcnt(6)
	v_pk_add_f32 v[6:7], v[10:11], v[12:13]
	v_pk_add_f32 v[4:5], v[4:5], 0 op_sel_hi:[1,0]
	s_waitcnt vmcnt(5)
	v_pk_add_f32 v[10:11], v[14:15], v[16:17]
	v_pk_add_f32 v[4:5], v[4:5], v[6:7]
	s_waitcnt vmcnt(4)
	v_pk_add_f32 v[12:13], v[18:19], v[20:21]
	v_pk_add_f32 v[4:5], v[4:5], v[10:11]
	s_nop 0
	v_pk_add_f32 v[4:5], v[4:5], v[12:13]
	ds_bpermute_b32 v6, v8, v4
	ds_bpermute_b32 v7, v8, v5
	s_and_saveexec_b64 s[8:9], vcc
	s_cbranch_execz .LBB0_1233
	s_waitcnt lgkmcnt(0)
	v_pk_add_f32 v[4:5], v[4:5], v[6:7]
	s_mov_b32 s4, 0x3a800000
	v_pk_mul_f32 v[4:5], v[4:5], s[4:5] op_sel_hi:[1,0]
	s_nop 0
	v_fma_f32 v5, -v4, v4, v5
	v_max_f32_e32 v5, 0, v5
	v_add_f32_e32 v5, 0x3727c5ac, v5
	v_rsq_f32_e32 v5, v5
	ds_write_b64 v9, v[4:5]
.LBB0_1233:
	s_or_b64 exec, exec, s[8:9]
	s_waitcnt lgkmcnt(0)
	s_waitcnt vmcnt(3)
	v_pk_add_f32 v[0:1], v[24:25], v[26:27]
	s_waitcnt vmcnt(2)
	v_pk_add_f32 v[2:3], v[28:29], v[30:31]
	v_pk_add_f32 v[0:1], v[0:1], 0 op_sel_hi:[1,0]
	s_waitcnt vmcnt(1)
	v_pk_add_f32 v[4:5], v[32:33], v[34:35]
	v_pk_add_f32 v[0:1], v[0:1], v[2:3]
	s_waitcnt vmcnt(0)
	v_pk_add_f32 v[6:7], v[36:37], v[38:39]
	v_pk_add_f32 v[0:1], v[0:1], v[4:5]
	s_nop 0
	v_pk_add_f32 v[0:1], v[0:1], v[6:7]
	ds_bpermute_b32 v2, v8, v0
	ds_bpermute_b32 v3, v8, v1
	s_and_saveexec_b64 s[0:1], vcc
	s_cbranch_execz .LBB0_1235
	s_waitcnt lgkmcnt(0)
	v_pk_add_f32 v[0:1], v[0:1], v[2:3]
	s_mov_b32 s4, 0x3a800000
	v_pk_mul_f32 v[0:1], v[0:1], s[4:5] op_sel_hi:[1,0]
	s_nop 0
	v_fma_f32 v1, -v0, v0, v1
	v_max_f32_e32 v1, 0, v1
	v_add_f32_e32 v1, 0x3727c5ac, v1
	v_rsq_f32_e32 v1, v1
	ds_write_b64 v9, v[0:1] offset:2048

; #define LAS __attribute__((address_space(3)))
;     __device__ bool next(int i, Unit& u) const { const int nr = nwg / G; if (i >= nr) return false; return RegSched::next(nr - 1 - i, u); }
;     template <class Sched> __device__ __forceinline__ void prep(const Sched& S, LAS unsigned char* ldsx) {
;         Unit u; int t0 = 0, t1 = 0; bool any = S.next(0, u);
;         if (any) { t0 = u.row0; t1 = t0; for (int i = 1; S.next(i, u); ++i) if (u.row0 != t0) { t1 = u.row0; break; } }
;         tag0 = t0;
;         if (any) {
;             LAS f32x2* X = (LAS f32x2*)ldsx; int t = threadIdx.x; asm volatile("" : "+v"(t));
; #pragma unroll
;             for (int e = 0; e < 2; ++e) { float s, q; stats_of(st_in, (size_t)(e ? t1 : t0) + (t >> 1), t & 1, s, q);
;                 s += __shfl_xor(s, 1); q += __shfl_xor(q, 1);
;                 const float mean = s * (1.f / DM);
;                 if ((t & 1) == 0) X[e * 256 + (t >> 1)] = (f32x2){mean, __builtin_amdgcn_rsqf(fmaxf(q * (1.f / DM) - mean * mean, 0.f) + LN_EPS)}; }
.LBB0_1354:
	v_mov_b32_e32 v2, v202
	s_ashr_i32 s11, s10, 31
	v_ashrrev_i32_e32 v0, 1, v2
	v_ashrrev_i32_e32 v1, 31, v0
	v_lshl_add_u64 v[4:5], v[0:1], 0, s[10:11]
	v_and_b32_e32 v22, 1, v2
	v_lshlrev_b64 v[4:5], 7, v[4:5]
	v_mov_b32_e32 v3, 0
	v_lshl_add_u64 v[4:5], s[90:91], 0, v[4:5]
	v_lshlrev_b32_e32 v2, 6, v22
	v_lshl_add_u64 v[8:9], v[4:5], 0, v[2:3]
	global_load_dwordx4 v[4:7], v[8:9], off
	global_load_dwordx4 v[10:13], v[8:9], off offset:16
	global_load_dwordx4 v[14:17], v[8:9], off offset:32
	global_load_dwordx4 v[18:21], v[8:9], off offset:48
	s_mov_b32 s98, s0
	s_ashr_i32 s99, s0, 31
	v_lshl_add_u64 v[40:41], v[0:1], 0, s[98:99]
	v_lshlrev_b64 v[40:41], 7, v[40:41]
	v_lshl_add_u64 v[40:41], s[90:91], 0, v[40:41]
	v_lshlrev_b32_e32 v42, 6, v22
	v_mov_b32_e32 v43, 0
	v_lshl_add_u64 v[40:41], v[40:41], 0, v[42:43]
	global_load_dwordx4 v[24:27], v[40:41], off
	global_load_dwordx4 v[28:31], v[40:41], off offset:16
	global_load_dwordx4 v[32:35], v[40:41], off offset:32
	global_load_dwordx4 v[36:39], v[40:41], off offset:48
	v_mbcnt_lo_u32_b32 v2, -1, 0
	v_mbcnt_hi_u32_b32 v2, -1, v2
	v_and_b32_e32 v9, 64, v2
	v_xor_b32_e32 v8, 1, v2
	v_add_u32_e32 v9, 64, v9
	v_cmp_lt_i32_e32 vcc, v8, v9
	s_add_i32 s1, 0, 0x20000
	v_lshl_add_u32 v9, v0, 3, s1
	v_cndmask_b32_e32 v2, v2, v8, vcc
	v_lshlrev_b32_e32 v8, 2, v2
	v_lshlrev_b32_e32 v2, 3, v22
	v_cmp_eq_u32_e32 vcc, 0, v22
	s_waitcnt vmcnt(7)
	v_pk_add_f32 v[4:5], v[4:5], v[6:7]
	s_waitcnt vmcnt(6)
	v_pk_add_f32 v[6:7], v[10:11], v[12:13]
	v_pk_add_f32 v[4:5], v[4:5], 0 op_sel_hi:[1,0]
	s_waitcnt vmcnt(5)
	v_pk_add_f32 v[10:11], v[14:15], v[16:17]
	v_pk_add_f32 v[4:5], v[4:5], v[6:7]
	s_waitcnt vmcnt(4)
	v_pk_add_f32 v[12:13], v[18:19], v[20:21]
	v_pk_add_f32 v[4:5], v[4:5], v[10:11]
	s_nop 0
	v_pk_add_f32 v[4:5], v[4:5], v[12:13]
	ds_bpermute_b32 v6, v8, v4
	ds_bpermute_b32 v7, v8, v5
	s_and_saveexec_b64 s[8:9], vcc
	s_cbranch_execz .LBB0_1356
	s_waitcnt lgkmcnt(0)
	v_pk_add_f32 v[4:5], v[4:5], v[6:7]
	s_mov_b32 s4, 0x3a800000
	v_pk_mul_f32 v[4:5], v[4:5], s[4:5] op_sel_hi:[1,0]
	s_nop 0
	v_fma_f32 v5, -v4, v4, v5
	v_max_f32_e32 v5, 0, v5
	v_add_f32_e32 v5, 0x3727c5ac, v5
	v_rsq_f32_e32 v5, v5
	ds_write_b64 v9, v[4:5]

; #define LAS __attribute__((address_space(3)))
;     __device__ bool next(int i, Unit& u) const { const int nr = nwg / G; if (i >= nr) return false; return RegSched::next(nr - 1 - i, u); }
;     template <class Sched> __device__ __forceinline__ void prep(const Sched& S, LAS unsigned char* ldsx) {
;         Unit u; int t0 = 0, t1 = 0; bool any = S.next(0, u);
;         if (any) { t0 = u.row0; t1 = t0; for (int i = 1; S.next(i, u); ++i) if (u.row0 != t0) { t1 = u.row0; break; } }
;         tag0 = t0;
;         if (any) {
;             LAS f32x2* X = (LAS f32x2*)ldsx; int t = threadIdx.x; asm volatile("" : "+v"(t));
; #pragma unroll
;             for (int e = 0; e < 2; ++e) { float s, q; stats_of(st_in, (size_t)(e ? t1 : t0) + (t >> 1), t & 1, s, q);
;                 s += __shfl_xor(s, 1); q += __shfl_xor(q, 1);
;                 const float mean = s * (1.f / DM);
;                 if ((t & 1) == 0) X[e * 256 + (t >> 1)] = (f32x2){mean, __builtin_amdgcn_rsqf(fmaxf(q * (1.f / DM) - mean * mean, 0.f) + LN_EPS)}; }
.LBB0_1455:
	v_mov_b32_e32 v2, v202
	s_ashr_i32 s9, s8, 31
	v_ashrrev_i32_e32 v0, 1, v2
	v_ashrrev_i32_e32 v1, 31, v0
	v_lshl_add_u64 v[4:5], v[0:1], 0, s[8:9]
	v_and_b32_e32 v22, 1, v2
	v_lshlrev_b64 v[4:5], 7, v[4:5]
	v_mov_b32_e32 v3, 0
	v_lshl_add_u64 v[4:5], s[90:91], 0, v[4:5]
	v_lshlrev_b32_e32 v2, 6, v22
	v_lshl_add_u64 v[8:9], v[4:5], 0, v[2:3]
	global_load_dwordx4 v[4:7], v[8:9], off
	global_load_dwordx4 v[10:13], v[8:9], off offset:16
	global_load_dwordx4 v[14:17], v[8:9], off offset:32
	global_load_dwordx4 v[18:21], v[8:9], off offset:48
	s_mov_b32 s98, s0
	s_ashr_i32 s99, s0, 31
	v_lshl_add_u64 v[40:41], v[0:1], 0, s[98:99]
	v_lshlrev_b64 v[40:41], 7, v[40:41]
	v_lshl_add_u64 v[40:41], s[90:91], 0, v[40:41]
	v_lshlrev_b32_e32 v42, 6, v22
	v_mov_b32_e32 v43, 0
	v_lshl_add_u64 v[40:41], v[40:41], 0, v[42:43]
	global_load_dwordx4 v[24:27], v[40:41], off
	global_load_dwordx4 v[28:31], v[40:41], off offset:16
	global_load_dwordx4 v[32:35], v[40:41], off offset:32
	global_load_dwordx4 v[36:39], v[40:41], off offset:48
	v_mbcnt_lo_u32_b32 v2, -1, 0
	v_mbcnt_hi_u32_b32 v2, -1, v2
	v_and_b32_e32 v9, 64, v2
	v_xor_b32_e32 v8, 1, v2
	v_add_u32_e32 v9, 64, v9
	v_cmp_lt_i32_e32 vcc, v8, v9
	s_add_i32 s1, 0, 0x20000
	v_lshl_add_u32 v9, v0, 3, s1
	v_cndmask_b32_e32 v2, v2, v8, vcc
	v_lshlrev_b32_e32 v8, 2, v2
	v_lshlrev_b32_e32 v2, 3, v22
	v_cmp_eq_u32_e32 vcc, 0, v22
	s_waitcnt vmcnt(7)
	v_pk_add_f32 v[4:5], v[4:5], v[6:7]
	s_waitcnt vmcnt(6)
	v_pk_add_f32 v[6:7], v[10:11], v[12:13]
	v_pk_add_f32 v[4:5], v[4:5], 0 op_sel_hi:[1,0]
	s_waitcnt vmcnt(5)
	v_pk_add_f32 v[10:11], v[14:15], v[16:17]
	v_pk_add_f32 v[4:5], v[4:5], v[6:7]
	s_waitcnt vmcnt(4)
	v_pk_add_f32 v[12:13], v[18:19], v[20:21]
	v_pk_add_f32 v[4:5], v[4:5], v[10:11]
	s_nop 0
	v_pk_add_f32 v[4:5], v[4:5], v[12:13]
	ds_bpermute_b32 v6, v8, v4
	ds_bpermute_b32 v7, v8, v5
	s_and_saveexec_b64 s[10:11], vcc
	s_cbranch_execz .LBB0_1457
	s_waitcnt lgkmcnt(0)
	v_pk_add_f32 v[4:5], v[4:5], v[6:7]
	s_mov_b32 s4, 0x3a800000
	v_pk_mul_f32 v[4:5], v[4:5], s[4:5] op_sel_hi:[1,0]
	s_nop 0
	v_fma_f32 v5, -v4, v4, v5
	v_max_f32_e32 v5, 0, v5
	v_add_f32_e32 v5, 0x3727c5ac, v5
	v_rsq_f32_e32 v5, v5
	ds_write_b64 v9, v[4:5]

;     __device__ __forceinline__ void operator()(const f32x4 (&acc)[2][2][4][2], const Unit& u, int wr, int wc, int fr_, int fq_, LAS unsigned char* ldsx) const {
;     ...
;             if constexpr (PROD) { s += __shfl_xor(s, 16); ss += __shfl_xor(ss, 16); s += __shfl_xor(s, 32); ss += __shfl_xor(ss, 32);
;                 if (fq == 0) st_out[row * 16 + (u.col0 >> 8) * 4 + wc] = (f32x2){s, ss}; }
.Lln3_nopub:
	s_waitcnt vmcnt(0)
	s_barrier
	v_cmp_eq_u32_e64 s[100:101], 0, v202
	s_mov_b64 exec, s[100:101]
	s_cbranch_execz .Lln3_skip
	v_mov_b32_e32 v80, s20
	v_lshrrev_b32_e32 v80, 8, v80
	v_lshlrev_b32_e32 v80, 2, v80
	v_add_u32_e32 v80, 0x3800, v80
	v_mov_b32_e32 v81, 1
	global_atomic_add v82, v80, v81, s[58:59] sc0
	s_waitcnt vmcnt(0)
	v_readfirstlane_b32 s101, v82
	s_cmp_ge_u32 s101, 3
	s_cbranch_scc1 .Lln3_skip
	s_mov_b32 s100, 0
